# mixa QK section: K-fragment reads 3-deep read-ahead through 4 dead register quads with counted lgkmcnt (was ds_read, lgkmcnt(0), MFMA chains), on top of the counted vmcnt waits
# baseline (speedup 1.0000x reference)
; #define SBAR() __builtin_amdgcn_sched_barrier(0)
; __device__ __forceinline__ void mixa_run(int b, int h, int br, int res, int n0, const bf16_t* __restrict__ proj, const float* __restrict__ btab,
;                                          bf16_t* __restrict__ OA, float* __restrict__ LSE, char* lds) {
;     ...
;     f32x16 p[5];
; #pragma unroll
;     for (int kb = 0; kb < 5; ++kb) { p[kb] = f32x16{}; const int brow = q32 + kb; const int sl = ((2 * s + (brow >> 1)) & 3) * 16384 + (brow & 1) * 8192;
; #pragma unroll
;       for (int d0 = 0; d0 < 8; ++d0) { const int cb = (d0 * 16 + hi * 8) * 2;
;         const bf16x8 a = *reinterpret_cast<const bf16x8*>(K_lds + sl + KSWZ(r32, cb));
;         p[kb] = __builtin_amdgcn_mfma_f32_32x32x16_bf16(a, qr[d0], p[kb], 0, 0, 0); }
;       SBAR(); }
.Lmixa_qk:
	s_add_i32 s68, s39, s22
	s_and_b32 s16, s68, 0xc000
	v_add_u32_e32 v115, s16, v217
	v_add_u32_e32 v117, v115, v216
	ds_read_b128 v[164:167], v117
	v_add_u32_e32 v117, v115, v218
	ds_read_b128 v[168:171], v117
	v_add_u32_e32 v117, v115, v219
	ds_read_b128 v[172:175], v117
	s_waitcnt lgkmcnt(2)
	v_mfma_f32_32x32x16_bf16 v[66:81], v[164:167], v[118:121], 0
	v_add_u32_e32 v117, v115, v220
	ds_read_b128 v[176:179], v117
	s_waitcnt lgkmcnt(2)
	v_mfma_f32_32x32x16_bf16 v[66:81], v[168:171], v[122:125], v[66:81]
	v_add_u32_e32 v117, v115, v221
	ds_read_b128 v[164:167], v117
	s_waitcnt lgkmcnt(2)
	v_mfma_f32_32x32x16_bf16 v[66:81], v[172:175], v[126:129], v[66:81]
	v_add_u32_e32 v117, v115, v222
	ds_read_b128 v[168:171], v117
	s_waitcnt lgkmcnt(2)
	v_mfma_f32_32x32x16_bf16 v[66:81], v[176:179], v[130:133], v[66:81]
	v_add_u32_e32 v117, v115, v223
	ds_read_b128 v[172:175], v117
	s_waitcnt lgkmcnt(2)
	v_mfma_f32_32x32x16_bf16 v[66:81], v[164:167], v[134:137], v[66:81]
	v_add_u32_e32 v117, v115, v224
	ds_read_b128 v[176:179], v117
	s_waitcnt lgkmcnt(2)
	v_mfma_f32_32x32x16_bf16 v[66:81], v[168:171], v[138:141], v[66:81]
	s_add_i32 s16, s23, s22
	s_and_b32 s69, s16, 0xc000
	v_add_u32_e32 v116, s69, v225
	v_add_u32_e32 v117, v116, v216
	ds_read_b128 v[164:167], v117
	s_waitcnt lgkmcnt(2)
	v_mfma_f32_32x32x16_bf16 v[66:81], v[172:175], v[142:145], v[66:81]
	v_add_u32_e32 v117, v116, v218
	ds_read_b128 v[168:171], v117
	s_waitcnt lgkmcnt(2)
	v_mfma_f32_32x32x16_bf16 v[66:81], v[176:179], v[146:149], v[66:81]
	v_add_u32_e32 v117, v116, v219
	ds_read_b128 v[172:175], v117
	s_waitcnt lgkmcnt(2)
	v_mfma_f32_32x32x16_bf16 v[50:65], v[164:167], v[118:121], 0
	v_add_u32_e32 v117, v116, v220
	ds_read_b128 v[176:179], v117
	s_waitcnt lgkmcnt(2)
	v_mfma_f32_32x32x16_bf16 v[50:65], v[168:171], v[122:125], v[50:65]
	v_add_u32_e32 v117, v116, v221
	ds_read_b128 v[164:167], v117
	s_waitcnt lgkmcnt(2)
	v_mfma_f32_32x32x16_bf16 v[50:65], v[172:175], v[126:129], v[50:65]
	v_add_u32_e32 v117, v116, v222
	ds_read_b128 v[168:171], v117
	s_waitcnt lgkmcnt(2)
	v_mfma_f32_32x32x16_bf16 v[50:65], v[176:179], v[130:133], v[50:65]
	v_add_u32_e32 v117, v116, v223
	ds_read_b128 v[172:175], v117
	s_waitcnt lgkmcnt(2)
	v_mfma_f32_32x32x16_bf16 v[50:65], v[164:167], v[134:137], v[50:65]
	v_add_u32_e32 v117, v116, v224
	ds_read_b128 v[176:179], v117
	s_waitcnt lgkmcnt(2)
	v_mfma_f32_32x32x16_bf16 v[50:65], v[168:171], v[138:141], v[50:65]
	s_add_i32 s16, s3, s22
	s_and_b32 s25, s16, 0xc000
	v_add_u32_e32 v115, s25, v226
	v_add_u32_e32 v117, v115, v216
	ds_read_b128 v[164:167], v117
	s_waitcnt lgkmcnt(2)
	v_mfma_f32_32x32x16_bf16 v[50:65], v[172:175], v[142:145], v[50:65]
	v_add_u32_e32 v117, v115, v218
	ds_read_b128 v[168:171], v117
	s_waitcnt lgkmcnt(2)
	v_mfma_f32_32x32x16_bf16 v[50:65], v[176:179], v[146:149], v[50:65]
	v_add_u32_e32 v117, v115, v219
	ds_read_b128 v[172:175], v117
	s_waitcnt lgkmcnt(2)
	v_mfma_f32_32x32x16_bf16 v[34:49], v[164:167], v[118:121], 0
	v_add_u32_e32 v117, v115, v220
	ds_read_b128 v[176:179], v117
	s_waitcnt lgkmcnt(2)
	v_mfma_f32_32x32x16_bf16 v[34:49], v[168:171], v[122:125], v[34:49]
	v_add_u32_e32 v117, v115, v221
	ds_read_b128 v[164:167], v117
	s_waitcnt lgkmcnt(2)
	v_mfma_f32_32x32x16_bf16 v[34:49], v[172:175], v[126:129], v[34:49]
	v_add_u32_e32 v117, v115, v222
	ds_read_b128 v[168:171], v117
	s_waitcnt lgkmcnt(2)
	v_mfma_f32_32x32x16_bf16 v[34:49], v[176:179], v[130:133], v[34:49]
	v_add_u32_e32 v117, v115, v223
	ds_read_b128 v[172:175], v117
	s_waitcnt lgkmcnt(2)
	v_mfma_f32_32x32x16_bf16 v[34:49], v[164:167], v[134:137], v[34:49]
	v_add_u32_e32 v117, v115, v224
	ds_read_b128 v[176:179], v117
	s_waitcnt lgkmcnt(2)
	v_mfma_f32_32x32x16_bf16 v[34:49], v[168:171], v[138:141], v[34:49]
	s_add_i32 s16, s2, s22
	s_and_b32 s26, s16, 0xc000
	v_add_u32_e32 v116, s26, v227
	v_add_u32_e32 v117, v116, v216
	ds_read_b128 v[164:167], v117
	s_waitcnt lgkmcnt(2)
	v_mfma_f32_32x32x16_bf16 v[34:49], v[172:175], v[142:145], v[34:49]
	v_add_u32_e32 v117, v116, v218
	ds_read_b128 v[168:171], v117
	s_waitcnt lgkmcnt(2)
	v_mfma_f32_32x32x16_bf16 v[34:49], v[176:179], v[146:149], v[34:49]
	v_add_u32_e32 v117, v116, v219
	ds_read_b128 v[172:175], v117
	s_waitcnt lgkmcnt(2)
	v_mfma_f32_32x32x16_bf16 v[18:33], v[164:167], v[118:121], 0
	v_add_u32_e32 v117, v116, v220
	ds_read_b128 v[176:179], v117
	s_waitcnt lgkmcnt(2)
	v_mfma_f32_32x32x16_bf16 v[18:33], v[168:171], v[122:125], v[18:33]
	v_add_u32_e32 v117, v116, v221
	ds_read_b128 v[164:167], v117
	s_waitcnt lgkmcnt(2)
	v_mfma_f32_32x32x16_bf16 v[18:33], v[172:175], v[126:129], v[18:33]
	v_add_u32_e32 v117, v116, v222
	ds_read_b128 v[168:171], v117
	s_waitcnt lgkmcnt(2)
	v_mfma_f32_32x32x16_bf16 v[18:33], v[176:179], v[130:133], v[18:33]
	v_add_u32_e32 v117, v116, v223
	ds_read_b128 v[172:175], v117
	s_waitcnt lgkmcnt(2)
	v_mfma_f32_32x32x16_bf16 v[18:33], v[164:167], v[134:137], v[18:33]
	v_add_u32_e32 v117, v116, v224
	ds_read_b128 v[176:179], v117
	s_waitcnt lgkmcnt(2)
	v_mfma_f32_32x32x16_bf16 v[18:33], v[168:171], v[138:141], v[18:33]
	s_add_i32 s16, s48, s22
	s_and_b32 s16, s16, 0xc000
	v_add_u32_e32 v115, s16, v217
	v_add_u32_e32 v117, v115, v216
	ds_read_b128 v[164:167], v117
	s_waitcnt lgkmcnt(2)
	v_mfma_f32_32x32x16_bf16 v[18:33], v[172:175], v[142:145], v[18:33]
	v_add_u32_e32 v117, v115, v218
	ds_read_b128 v[168:171], v117
	s_waitcnt lgkmcnt(2)
	v_mfma_f32_32x32x16_bf16 v[18:33], v[176:179], v[146:149], v[18:33]
	v_add_u32_e32 v117, v115, v219
	ds_read_b128 v[172:175], v117
	s_waitcnt lgkmcnt(2)
	v_mfma_f32_32x32x16_bf16 v[2:17], v[164:167], v[118:121], 0
	v_add_u32_e32 v117, v115, v220
	ds_read_b128 v[176:179], v117
	s_waitcnt lgkmcnt(2)
	v_mfma_f32_32x32x16_bf16 v[2:17], v[168:171], v[122:125], v[2:17]
	v_add_u32_e32 v117, v115, v221
	ds_read_b128 v[164:167], v117
	s_waitcnt lgkmcnt(2)
	v_mfma_f32_32x32x16_bf16 v[2:17], v[172:175], v[126:129], v[2:17]
	v_add_u32_e32 v117, v115, v222
	ds_read_b128 v[168:171], v117
	s_waitcnt lgkmcnt(2)
	v_mfma_f32_32x32x16_bf16 v[2:17], v[176:179], v[130:133], v[2:17]
	v_add_u32_e32 v117, v115, v223
	ds_read_b128 v[172:175], v117
	s_waitcnt lgkmcnt(2)
	v_mfma_f32_32x32x16_bf16 v[2:17], v[164:167], v[134:137], v[2:17]
	v_add_u32_e32 v117, v115, v224
	ds_read_b128 v[176:179], v117
	s_waitcnt lgkmcnt(2)
	v_mfma_f32_32x32x16_bf16 v[2:17], v[168:171], v[138:141], v[2:17]
	s_waitcnt lgkmcnt(1)
	v_mfma_f32_32x32x16_bf16 v[2:17], v[172:175], v[142:145], v[2:17]
	s_waitcnt lgkmcnt(0)
	v_mfma_f32_32x32x16_bf16 v[2:17], v[176:179], v[146:149], v[2:17]
	v_cndmask_b32_e64 v115, 0, 1, s[12:13]
	v_cmp_ne_u32_e64 s[42:43], 1, v115
	s_andn2_b64 vcc, exec, s[12:13]
	v_lshl_add_u64 v[116:117], v[158:159], 0, s[10:11]
	s_cbranch_vccnz .LBB0_319
; __device__ __forceinline__ void mixa_run(int b, int h, int br, int res, int n0, const bf16_t* __restrict__ proj, const float* __restrict__ btab,
;                                          bf16_t* __restrict__ OA, float* __restrict__ LSE, char* lds) {
;     ...
;     const size_t tokq = rowb + ((size_t)(64 * nq + 32 * q32 + r32) << sh) + res;
;     if (more) { const bf16_t* Qp = proj + (tokq + ((size_t)128 << sh)) * INW + h * 128 + hi * 8;
; #pragma unroll
;       for (int d0 = 0; d0 < 8; ++d0) qr[d0] = ld8(Qp + d0 * 16); }
	v_lshl_add_u64 v[118:119], v[116:117], 0, s[64:65]
	v_lshlrev_b64 v[118:119], s29, v[118:119]
	v_lshl_add_u64 v[118:119], v[118:119], 0, s[46:47]
	v_mad_u64_u32 v[146:147], s[12:13], v118, s1, v[154:155]
	v_mov_b32_e32 v118, v147
	v_mad_u64_u32 v[118:119], s[12:13], v119, s1, v[118:119]
	v_mov_b32_e32 v147, v118
	global_load_dwordx4 v[118:121], v[146:147], off
	global_load_dwordx4 v[122:125], v[146:147], off offset:32
	global_load_dwordx4 v[126:129], v[146:147], off offset:64
	global_load_dwordx4 v[130:133], v[146:147], off offset:96
	global_load_dwordx4 v[134:137], v[146:147], off offset:128
	global_load_dwordx4 v[138:141], v[146:147], off offset:160
	global_load_dwordx4 v[142:145], v[146:147], off offset:192
	s_nop 0
	global_load_dwordx4 v[146:149], v[146:147], off offset:224
